# v26canon
# speedup vs baseline: 1.0052x; 1.0028x over previous
.LBB0_179:
	s_or_b64 exec, exec, s[78:79]
	v_max_f32_e32 v1, v76, v77
	v_max_f32_e32 v112, v92, v93
	v_max3_f32 v1, v74, v75, v1
	v_max3_f32 v112, v90, v91, v112
	v_max3_f32 v1, v1, s41, v112
	v_max_f32_e32 v112, v80, v81
	v_max_f32_e32 v114, v96, v96
	v_max_f32_e32 v113, v114, v97
	v_max3_f32 v112, v78, v79, v112
	v_max3_f32 v113, v94, v95, v113
	v_max3_f32 v1, v1, v112, v113
	ds_bpermute_b32 v112, v135, v1
	s_waitcnt lgkmcnt(0)
	v_max_f32_e32 v1, v1, v112
	ds_bpermute_b32 v112, v101, v1
	s_waitcnt lgkmcnt(0)
	v_max3_f32 v1, v111, v1, v112
	v_sub_f32_e32 v74, v74, v1
	v_sub_f32_e32 v112, v111, v1
	v_exp_f32_e32 v111, v74
	v_sub_f32_e32 v74, v75, v1
	v_exp_f32_e32 v113, v74
	v_sub_f32_e32 v74, v76, v1
	v_exp_f32_e32 v115, v74
	v_sub_f32_e32 v74, v77, v1
	v_exp_f32_e32 v117, v74
	v_sub_f32_e32 v74, v90, v1
	v_exp_f32_e32 v119, v74
	v_sub_f32_e32 v74, v91, v1
	v_exp_f32_e32 v91, v74
	v_sub_f32_e32 v74, v92, v1
	v_exp_f32_e32 v121, v74
	v_sub_f32_e32 v74, v93, v1
	v_exp_f32_e32 v93, v74
	v_sub_f32_e32 v74, v78, v1
	v_exp_f32_e32 v123, v74
	v_sub_f32_e32 v74, v79, v1
	v_exp_f32_e32 v125, v74
	v_sub_f32_e32 v74, v80, v1
	v_exp_f32_e32 v127, v74
	v_sub_f32_e32 v74, v81, v1
	v_exp_f32_e32 v129, v74
	v_sub_f32_e32 v74, v94, v1
	v_max_f32_e32 v90, v84, v85
	v_max_f32_e32 v92, v88, v89
	v_max3_f32 v90, v82, v83, v90
	v_max3_f32 v92, v86, v87, v92
	v_exp_f32_e32 v131, v74
	v_sub_f32_e32 v74, v95, v1
	v_max3_f32 v90, v90, s41, v92
	v_exp_f32_e32 v95, v74
	v_sub_f32_e32 v74, v96, v1
	v_max_f32_e32 v92, v68, v69
	v_max_f32_e32 v94, v72, v73
	v_max3_f32 v92, v66, v67, v92
	v_max3_f32 v94, v70, v71, v94
	v_max3_f32 v90, v90, v92, v94
	ds_bpermute_b32 v92, v135, v90
	v_exp_f32_e32 v134, v112
	v_exp_f32_e32 v133, v74
	v_sub_f32_e32 v74, v97, v1
	v_exp_f32_e32 v97, v74
	s_waitcnt lgkmcnt(0)
	v_max_f32_e32 v90, v90, v92
	ds_bpermute_b32 v92, v101, v90
	v_pk_mul_f32 v[80:81], v[52:53], v[134:135] op_sel_hi:[1,0]
	v_pk_mul_f32 v[78:79], v[50:51], v[134:135] op_sel_hi:[1,0]
	v_pk_mul_f32 v[76:77], v[56:57], v[134:135] op_sel_hi:[1,0]
	v_pk_mul_f32 v[74:75], v[54:55], v[134:135] op_sel_hi:[1,0]
	s_waitcnt lgkmcnt(0)
	v_max3_f32 v151, v110, v90, v92
	v_sub_f32_e32 v82, v82, v151
	v_sub_f32_e32 v152, v110, v151
	v_exp_f32_e32 v110, v82
	v_sub_f32_e32 v82, v83, v151
	v_exp_f32_e32 v112, v82
	v_sub_f32_e32 v82, v84, v151
	v_exp_f32_e32 v114, v82
	v_sub_f32_e32 v82, v85, v151
	v_sub_f32_e32 v66, v66, v151
	v_exp_f32_e32 v116, v82
	v_sub_f32_e32 v82, v86, v151
	v_exp_f32_e32 v122, v66
	v_sub_f32_e32 v66, v67, v151
	v_exp_f32_e32 v118, v82
	v_sub_f32_e32 v82, v87, v151
	v_exp_f32_e32 v124, v66
	v_pk_add_f32 v[66:67], v[110:111], 0 op_sel_hi:[1,0]
	v_exp_f32_e32 v90, v82
	v_sub_f32_e32 v82, v88, v151
	v_pk_add_f32 v[66:67], v[112:113], v[66:67]
	v_exp_f32_e32 v120, v82
	v_sub_f32_e32 v82, v89, v151
	v_pk_add_f32 v[66:67], v[114:115], v[66:67]
	v_exp_f32_e32 v92, v82
	v_pk_add_f32 v[66:67], v[116:117], v[66:67]
	v_sub_f32_e32 v68, v68, v151
	v_pk_add_f32 v[66:67], v[118:119], v[66:67]
	v_exp_f32_e32 v126, v68
	v_pk_add_f32 v[66:67], v[90:91], v[66:67]
	v_sub_f32_e32 v68, v69, v151
	v_pk_add_f32 v[66:67], v[120:121], v[66:67]
	v_exp_f32_e32 v128, v68
	v_pk_add_f32 v[66:67], v[92:93], v[66:67]
	v_sub_f32_e32 v68, v70, v151
	v_pk_add_f32 v[66:67], v[122:123], v[66:67]
	v_exp_f32_e32 v130, v68
	v_sub_f32_e32 v68, v71, v151
	v_pk_add_f32 v[66:67], v[124:125], v[66:67]
	v_exp_f32_e32 v94, v68
	v_sub_f32_e32 v68, v72, v151
	v_exp_f32_e32 v132, v68
	v_sub_f32_e32 v68, v73, v151
	v_pk_add_f32 v[66:67], v[126:127], v[66:67]
	v_exp_f32_e32 v96, v68
	v_pk_add_f32 v[66:67], v[128:129], v[66:67]
	v_exp_f32_e32 v82, v152
	v_pk_add_f32 v[66:67], v[130:131], v[66:67]
	v_mov_b32_e32 v83, v134
	v_pk_add_f32 v[66:67], v[94:95], v[66:67]
	v_add_u32_e32 v86, v150, v144
	v_pk_add_f32 v[66:67], v[132:133], v[66:67]
	v_pk_mul_f32 v[68:69], v[36:37], v[82:83] op_sel_hi:[1,0]
	v_pk_add_f32 v[66:67], v[96:97], v[66:67]
	v_pk_mul_f32 v[72:73], v[40:41], v[82:83] op_sel_hi:[1,0]
	v_pk_fma_f32 v[104:105], v[104:105], v[82:83], v[66:67]
	v_pk_mul_f32 v[66:67], v[34:35], v[82:83] op_sel_hi:[1,0]
	v_pk_mul_f32 v[70:71], v[38:39], v[82:83] op_sel_hi:[1,0]
	v_pk_mul_f32 v[44:45], v[44:45], v[82:83] op_sel_hi:[1,0]
	v_pk_mul_f32 v[42:43], v[42:43], v[82:83] op_sel_hi:[1,0]
	v_pk_mul_f32 v[36:37], v[48:49], v[82:83] op_sel_hi:[1,0]
	v_pk_mul_f32 v[34:35], v[46:47], v[82:83] op_sel_hi:[1,0]
	v_add_u32_e32 v186, v150, v144
	ds_read_b128 v[154:157], v186 offset:25088
	ds_read_b128 v[158:161], v186 offset:27136
	ds_read_b128 v[162:165], v186 offset:29184
	ds_read_b128 v[166:169], v186 offset:31232
	v_add_u32_e32 v187, v150, v146
	ds_read_b128 v[170:173], v187 offset:27136
	ds_read_b128 v[174:177], v187 offset:25088
	ds_read_b128 v[178:181], v187 offset:29184
	ds_read_b128 v[182:185], v187 offset:31232
	v_cvt_pk_bf16_f32 v54, v111, v113
	v_cvt_pk_bf16_f32 v55, v115, v117
	v_cvt_pk_bf16_f32 v56, v119, v91
	v_cvt_pk_bf16_f32 v57, v121, v93
	v_cvt_pk_bf16_f32 v38, v110, v112
	v_cvt_pk_bf16_f32 v39, v114, v116
	v_cvt_pk_bf16_f32 v40, v118, v90
	v_cvt_pk_bf16_f32 v41, v120, v92
	v_pk_mul_f32 v[60:61], v[60:61], v[134:135] op_sel_hi:[1,0]
	s_waitcnt lgkmcnt(7)
	v_mfma_f32_16x16x32_bf16 v[78:81], v[154:157], v[54:57], v[78:81]
	v_mul_f32_e64 v58, v58, v134
	v_mul_f32_e64 v59, v59, v134
	v_pk_mul_f32 v[52:53], v[64:65], v[134:135] op_sel_hi:[1,0]
	v_pk_mul_f32 v[50:51], v[62:63], v[134:135] op_sel_hi:[1,0]
	v_mfma_f32_16x16x32_bf16 v[66:69], v[154:157], v[38:41], v[66:69]
	v_add_u32_e32 v90, v150, v146
	v_cvt_pk_bf16_f32 v62, v123, v125
	s_waitcnt lgkmcnt(6)
	v_mfma_f32_16x16x32_bf16 v[74:77], v[158:161], v[54:57], v[74:77]
	v_cvt_pk_bf16_f32 v63, v127, v129
	v_cvt_pk_bf16_f32 v64, v131, v95
	v_cvt_pk_bf16_f32 v65, v133, v97
	v_mfma_f32_16x16x32_bf16 v[70:73], v[158:161], v[38:41], v[70:73]
	v_cvt_pk_bf16_f32 v46, v122, v124
	v_cvt_pk_bf16_f32 v47, v126, v128
	s_waitcnt lgkmcnt(5)
	v_mfma_f32_16x16x32_bf16 v[58:61], v[162:165], v[54:57], v[58:61]
	v_cvt_pk_bf16_f32 v48, v130, v94
	v_cvt_pk_bf16_f32 v49, v132, v96
	v_mov_b32_e32 v110, v151
	v_mfma_f32_16x16x32_bf16 v[42:45], v[162:165], v[38:41], v[42:45]
	v_mov_b32_e32 v111, v1
	s_waitcnt lgkmcnt(4)
	v_mfma_f32_16x16x32_bf16 v[86:89], v[166:169], v[54:57], v[50:53]
	v_mfma_f32_16x16x32_bf16 v[82:85], v[166:169], v[38:41], v[34:37]
	s_waitcnt lgkmcnt(2)
	v_mfma_f32_16x16x32_bf16 v[50:53], v[174:177], v[62:65], v[78:81]
	v_mfma_f32_16x16x32_bf16 v[34:37], v[174:177], v[46:49], v[66:69]
	s_waitcnt lgkmcnt(1)
	v_mfma_f32_16x16x32_bf16 v[58:61], v[178:181], v[62:65], v[58:61]
	v_mfma_f32_16x16x32_bf16 v[42:45], v[178:181], v[46:49], v[42:45]
	v_mfma_f32_16x16x32_bf16 v[54:57], v[170:173], v[62:65], v[74:77]
	v_mfma_f32_16x16x32_bf16 v[38:41], v[170:173], v[46:49], v[70:73]
	s_waitcnt lgkmcnt(0)
	v_mfma_f32_16x16x32_bf16 v[62:65], v[182:185], v[62:65], v[86:89]
	v_mfma_f32_16x16x32_bf16 v[46:49], v[182:185], v[46:49], v[82:85]

.LBB0_188:
	s_or_b64 exec, exec, s[78:79]
	v_max_f32_e32 v1, v68, v69
	v_max_f32_e32 v112, v92, v93
	v_max3_f32 v1, v66, v67, v1
	v_max3_f32 v112, v90, v91, v112
	v_max3_f32 v1, v1, s41, v112
	v_max_f32_e32 v112, v84, v85
	v_max_f32_e32 v114, v96, v96
	v_max_f32_e32 v113, v114, v97
	v_max3_f32 v112, v82, v83, v112
	v_max3_f32 v113, v94, v95, v113
	v_max3_f32 v1, v1, v112, v113
	ds_bpermute_b32 v112, v135, v1
	s_waitcnt lgkmcnt(0)
	v_max_f32_e32 v1, v1, v112
	ds_bpermute_b32 v112, v101, v1
	s_waitcnt lgkmcnt(0)
	v_max3_f32 v1, v111, v1, v112
	v_sub_f32_e32 v66, v66, v1
	v_sub_f32_e32 v112, v111, v1
	v_exp_f32_e32 v111, v66
	v_sub_f32_e32 v66, v67, v1
	v_exp_f32_e32 v113, v66
	v_sub_f32_e32 v66, v68, v1
	v_exp_f32_e32 v115, v66
	v_sub_f32_e32 v66, v69, v1
	v_exp_f32_e32 v117, v66
	v_sub_f32_e32 v66, v90, v1
	v_exp_f32_e32 v119, v66
	v_sub_f32_e32 v66, v91, v1
	v_exp_f32_e32 v91, v66
	v_sub_f32_e32 v66, v92, v1
	v_exp_f32_e32 v121, v66
	v_sub_f32_e32 v66, v93, v1
	v_exp_f32_e32 v93, v66
	v_sub_f32_e32 v66, v82, v1
	v_exp_f32_e32 v123, v66
	v_sub_f32_e32 v66, v83, v1
	v_exp_f32_e32 v125, v66
	v_sub_f32_e32 v66, v84, v1
	v_exp_f32_e32 v127, v66
	v_sub_f32_e32 v66, v85, v1
	v_exp_f32_e32 v129, v66
	v_sub_f32_e32 v66, v94, v1
	v_max_f32_e32 v90, v88, v89
	v_max_f32_e32 v92, v76, v77
	v_max3_f32 v90, v86, v87, v90
	v_max3_f32 v92, v74, v75, v92
	v_exp_f32_e32 v131, v66
	v_sub_f32_e32 v66, v95, v1
	v_max3_f32 v90, v90, s41, v92
	v_exp_f32_e32 v95, v66
	v_sub_f32_e32 v66, v96, v1
	v_max_f32_e32 v92, v72, v73
	v_max_f32_e32 v94, v80, v81
	v_max3_f32 v92, v70, v71, v92
	v_max3_f32 v94, v78, v79, v94
	v_max3_f32 v90, v90, v92, v94
	ds_bpermute_b32 v92, v135, v90
	v_exp_f32_e32 v152, v112
	v_exp_f32_e32 v133, v66
	v_sub_f32_e32 v66, v97, v1
	v_exp_f32_e32 v97, v66
	s_waitcnt lgkmcnt(0)
	v_max_f32_e32 v90, v90, v92
	ds_bpermute_b32 v92, v101, v90
	v_pk_mul_f32 v[84:85], v[52:53], v[152:153] op_sel_hi:[1,0]
	v_pk_mul_f32 v[82:83], v[50:51], v[152:153] op_sel_hi:[1,0]
	v_pk_mul_f32 v[68:69], v[56:57], v[152:153] op_sel_hi:[1,0]
	v_pk_mul_f32 v[66:67], v[54:55], v[152:153] op_sel_hi:[1,0]
	s_waitcnt lgkmcnt(0)
	v_max3_f32 v134, v110, v90, v92
	v_sub_f32_e32 v86, v86, v134
	v_sub_f32_e32 v151, v110, v134
	v_exp_f32_e32 v110, v86
	v_sub_f32_e32 v86, v87, v134
	v_exp_f32_e32 v112, v86
	v_sub_f32_e32 v86, v88, v134
	v_sub_f32_e32 v74, v74, v134
	v_exp_f32_e32 v114, v86
	v_sub_f32_e32 v86, v89, v134
	v_exp_f32_e32 v118, v74
	v_sub_f32_e32 v74, v75, v134
	v_exp_f32_e32 v116, v86
	v_exp_f32_e32 v90, v74
	v_sub_f32_e32 v74, v76, v134
	v_sub_f32_e32 v70, v70, v134
	v_exp_f32_e32 v120, v74
	v_pk_add_f32 v[74:75], v[110:111], 0 op_sel_hi:[1,0]
	v_exp_f32_e32 v122, v70
	v_sub_f32_e32 v70, v71, v134
	v_pk_add_f32 v[74:75], v[112:113], v[74:75]
	v_exp_f32_e32 v124, v70
	v_sub_f32_e32 v70, v72, v134
	v_pk_add_f32 v[74:75], v[114:115], v[74:75]
	v_sub_f32_e32 v76, v77, v134
	v_exp_f32_e32 v126, v70
	v_sub_f32_e32 v70, v73, v134
	v_pk_add_f32 v[74:75], v[116:117], v[74:75]
	v_exp_f32_e32 v92, v76
	v_exp_f32_e32 v128, v70
	v_sub_f32_e32 v70, v78, v134
	v_pk_add_f32 v[74:75], v[118:119], v[74:75]
	v_exp_f32_e32 v130, v70
	v_sub_f32_e32 v70, v79, v134
	v_pk_add_f32 v[74:75], v[90:91], v[74:75]
	v_exp_f32_e32 v94, v70
	v_sub_f32_e32 v70, v80, v134
	v_pk_add_f32 v[74:75], v[120:121], v[74:75]
	v_exp_f32_e32 v132, v70
	v_sub_f32_e32 v70, v81, v134
	v_exp_f32_e32 v96, v70
	v_pk_add_f32 v[70:71], v[92:93], v[74:75]
	v_exp_f32_e32 v78, v151
	v_pk_add_f32 v[70:71], v[122:123], v[70:71]
	v_mov_b32_e32 v79, v152
	v_pk_add_f32 v[70:71], v[124:125], v[70:71]
	v_add_u32_e32 v86, v150, v144
	v_pk_add_f32 v[70:71], v[126:127], v[70:71]
	v_pk_mul_f32 v[76:77], v[36:37], v[78:79] op_sel_hi:[1,0]
	v_pk_add_f32 v[70:71], v[128:129], v[70:71]
	v_pk_mul_f32 v[74:75], v[34:35], v[78:79] op_sel_hi:[1,0]
	v_pk_add_f32 v[70:71], v[130:131], v[70:71]
	v_pk_mul_f32 v[72:73], v[40:41], v[78:79] op_sel_hi:[1,0]
	v_pk_add_f32 v[70:71], v[94:95], v[70:71]
	v_pk_mul_f32 v[44:45], v[44:45], v[78:79] op_sel_hi:[1,0]
	v_pk_add_f32 v[70:71], v[132:133], v[70:71]
	v_pk_mul_f32 v[42:43], v[42:43], v[78:79] op_sel_hi:[1,0]
	v_pk_add_f32 v[70:71], v[96:97], v[70:71]
	v_pk_mul_f32 v[36:37], v[48:49], v[78:79] op_sel_hi:[1,0]
	v_pk_fma_f32 v[104:105], v[104:105], v[78:79], v[70:71]
	v_pk_mul_f32 v[70:71], v[38:39], v[78:79] op_sel_hi:[1,0]
	v_pk_mul_f32 v[34:35], v[46:47], v[78:79] op_sel_hi:[1,0]
	v_add_u32_e32 v186, v150, v144
	ds_read_b128 v[154:157], v186 offset:33280
	ds_read_b128 v[158:161], v186 offset:35328
	ds_read_b128 v[162:165], v186 offset:37376
	ds_read_b128 v[166:169], v186 offset:39424
	v_add_u32_e32 v187, v150, v146
	ds_read_b128 v[170:173], v187 offset:35328
	ds_read_b128 v[174:177], v187 offset:33280
	ds_read_b128 v[178:181], v187 offset:37376
	ds_read_b128 v[182:185], v187 offset:39424
	v_cvt_pk_bf16_f32 v54, v111, v113
	v_cvt_pk_bf16_f32 v55, v115, v117
	v_cvt_pk_bf16_f32 v56, v119, v91
	v_cvt_pk_bf16_f32 v57, v121, v93
	v_cvt_pk_bf16_f32 v38, v110, v112
	v_cvt_pk_bf16_f32 v39, v114, v116
	v_cvt_pk_bf16_f32 v40, v118, v90
	v_cvt_pk_bf16_f32 v41, v120, v92
	v_pk_mul_f32 v[60:61], v[60:61], v[152:153] op_sel_hi:[1,0]
	s_waitcnt lgkmcnt(7)
	v_mfma_f32_16x16x32_bf16 v[82:85], v[154:157], v[54:57], v[82:85]
	v_mul_f32_e64 v58, v58, v152
	v_mul_f32_e64 v59, v59, v152
	v_pk_mul_f32 v[52:53], v[64:65], v[152:153] op_sel_hi:[1,0]
	v_pk_mul_f32 v[50:51], v[62:63], v[152:153] op_sel_hi:[1,0]
	v_mfma_f32_16x16x32_bf16 v[74:77], v[154:157], v[38:41], v[74:77]
	v_add_u32_e32 v90, v150, v146
	v_cvt_pk_bf16_f32 v62, v123, v125
	s_waitcnt lgkmcnt(6)
	v_mfma_f32_16x16x32_bf16 v[66:69], v[158:161], v[54:57], v[66:69]
	v_cvt_pk_bf16_f32 v63, v127, v129
	v_cvt_pk_bf16_f32 v64, v131, v95
	v_cvt_pk_bf16_f32 v65, v133, v97
	v_mfma_f32_16x16x32_bf16 v[70:73], v[158:161], v[38:41], v[70:73]
	v_cvt_pk_bf16_f32 v46, v122, v124
	v_cvt_pk_bf16_f32 v47, v126, v128
	s_waitcnt lgkmcnt(5)
	v_mfma_f32_16x16x32_bf16 v[58:61], v[162:165], v[54:57], v[58:61]
	v_cvt_pk_bf16_f32 v48, v130, v94
	v_cvt_pk_bf16_f32 v49, v132, v96
	v_mov_b32_e32 v110, v134
	v_mfma_f32_16x16x32_bf16 v[42:45], v[162:165], v[38:41], v[42:45]
	v_mov_b32_e32 v111, v1
	s_waitcnt lgkmcnt(4)
	v_mfma_f32_16x16x32_bf16 v[86:89], v[166:169], v[54:57], v[50:53]
	v_mfma_f32_16x16x32_bf16 v[78:81], v[166:169], v[38:41], v[34:37]
	s_waitcnt lgkmcnt(3)
	v_mfma_f32_16x16x32_bf16 v[54:57], v[170:173], v[62:65], v[66:69]
	s_waitcnt lgkmcnt(1)
	v_mfma_f32_16x16x32_bf16 v[58:61], v[178:181], v[62:65], v[58:61]
	v_mfma_f32_16x16x32_bf16 v[42:45], v[178:181], v[46:49], v[42:45]
	v_mfma_f32_16x16x32_bf16 v[50:53], v[174:177], v[62:65], v[82:85]
	v_mfma_f32_16x16x32_bf16 v[34:37], v[174:177], v[46:49], v[74:77]
	v_mfma_f32_16x16x32_bf16 v[38:41], v[170:173], v[46:49], v[70:73]
	s_waitcnt lgkmcnt(0)
	v_mfma_f32_16x16x32_bf16 v[62:65], v[182:185], v[62:65], v[86:89]
	v_mfma_f32_16x16x32_bf16 v[46:49], v[182:185], v[46:49], v[78:81]

.LBB0_211:
	s_or_b64 exec, exec, s[82:83]
	v_max_f32_e32 v1, v76, v77
	v_max_f32_e32 v112, v92, v93
	v_max3_f32 v1, v74, v75, v1
	v_max3_f32 v112, v90, v91, v112
	v_max3_f32 v1, v1, s41, v112
	v_max_f32_e32 v112, v80, v81
	v_max_f32_e32 v114, v96, v96
	v_max_f32_e32 v113, v114, v97
	v_max3_f32 v112, v78, v79, v112
	v_max3_f32 v113, v94, v95, v113
	v_max3_f32 v1, v1, v112, v113
	ds_bpermute_b32 v112, v135, v1
	s_waitcnt lgkmcnt(0)
	v_max_f32_e32 v1, v1, v112
	ds_bpermute_b32 v112, v101, v1
	s_waitcnt lgkmcnt(0)
	v_max3_f32 v1, v111, v1, v112
	v_sub_f32_e32 v74, v74, v1
	v_sub_f32_e32 v112, v111, v1
	v_exp_f32_e32 v111, v74
	v_sub_f32_e32 v74, v75, v1
	v_exp_f32_e32 v113, v74
	v_sub_f32_e32 v74, v76, v1
	v_exp_f32_e32 v115, v74
	v_sub_f32_e32 v74, v77, v1
	v_exp_f32_e32 v117, v74
	v_sub_f32_e32 v74, v90, v1
	v_exp_f32_e32 v119, v74
	v_sub_f32_e32 v74, v91, v1
	v_exp_f32_e32 v91, v74
	v_sub_f32_e32 v74, v92, v1
	v_exp_f32_e32 v121, v74
	v_sub_f32_e32 v74, v93, v1
	v_exp_f32_e32 v93, v74
	v_sub_f32_e32 v74, v78, v1
	v_exp_f32_e32 v123, v74
	v_sub_f32_e32 v74, v79, v1
	v_exp_f32_e32 v125, v74
	v_sub_f32_e32 v74, v80, v1
	v_exp_f32_e32 v127, v74
	v_sub_f32_e32 v74, v81, v1
	v_exp_f32_e32 v129, v74
	v_sub_f32_e32 v74, v94, v1
	v_max_f32_e32 v90, v84, v85
	v_max_f32_e32 v92, v88, v89
	v_max3_f32 v90, v82, v83, v90
	v_max3_f32 v92, v86, v87, v92
	v_exp_f32_e32 v131, v74
	v_sub_f32_e32 v74, v95, v1
	v_max3_f32 v90, v90, s41, v92
	v_exp_f32_e32 v95, v74
	v_sub_f32_e32 v74, v96, v1
	v_max_f32_e32 v92, v68, v69
	v_max_f32_e32 v94, v72, v73
	v_max3_f32 v92, v66, v67, v92
	v_max3_f32 v94, v70, v71, v94
	v_max3_f32 v90, v90, v92, v94
	ds_bpermute_b32 v92, v135, v90
	v_exp_f32_e32 v134, v112
	v_exp_f32_e32 v133, v74
	v_sub_f32_e32 v74, v97, v1
	v_exp_f32_e32 v97, v74
	s_waitcnt lgkmcnt(0)
	v_max_f32_e32 v90, v90, v92
	ds_bpermute_b32 v92, v101, v90
	v_pk_mul_f32 v[80:81], v[52:53], v[134:135] op_sel_hi:[1,0]
	v_pk_mul_f32 v[78:79], v[50:51], v[134:135] op_sel_hi:[1,0]
	v_pk_mul_f32 v[76:77], v[56:57], v[134:135] op_sel_hi:[1,0]
	v_pk_mul_f32 v[74:75], v[54:55], v[134:135] op_sel_hi:[1,0]
	s_waitcnt lgkmcnt(0)
	v_max3_f32 v152, v110, v90, v92
	v_sub_f32_e32 v82, v82, v152
	v_sub_f32_e32 v153, v110, v152
	v_exp_f32_e32 v110, v82
	v_sub_f32_e32 v82, v83, v152
	v_exp_f32_e32 v112, v82
	v_sub_f32_e32 v82, v84, v152
	v_exp_f32_e32 v114, v82
	v_sub_f32_e32 v82, v85, v152
	v_sub_f32_e32 v66, v66, v152
	v_exp_f32_e32 v116, v82
	v_sub_f32_e32 v82, v86, v152
	v_exp_f32_e32 v122, v66
	v_sub_f32_e32 v66, v67, v152
	v_exp_f32_e32 v118, v82
	v_sub_f32_e32 v82, v87, v152
	v_exp_f32_e32 v124, v66
	v_pk_add_f32 v[66:67], v[110:111], 0 op_sel_hi:[1,0]
	v_exp_f32_e32 v90, v82
	v_sub_f32_e32 v82, v88, v152
	v_pk_add_f32 v[66:67], v[112:113], v[66:67]
	v_exp_f32_e32 v120, v82
	v_sub_f32_e32 v82, v89, v152
	v_pk_add_f32 v[66:67], v[114:115], v[66:67]
	v_exp_f32_e32 v92, v82
	v_pk_add_f32 v[66:67], v[116:117], v[66:67]
	v_sub_f32_e32 v68, v68, v152
	v_pk_add_f32 v[66:67], v[118:119], v[66:67]
	v_exp_f32_e32 v126, v68
	v_pk_add_f32 v[66:67], v[90:91], v[66:67]
	v_sub_f32_e32 v68, v69, v152
	v_pk_add_f32 v[66:67], v[120:121], v[66:67]
	v_exp_f32_e32 v128, v68
	v_pk_add_f32 v[66:67], v[92:93], v[66:67]
	v_sub_f32_e32 v68, v70, v152
	v_pk_add_f32 v[66:67], v[122:123], v[66:67]
	v_exp_f32_e32 v130, v68
	v_sub_f32_e32 v68, v71, v152
	v_pk_add_f32 v[66:67], v[124:125], v[66:67]
	v_exp_f32_e32 v94, v68
	v_sub_f32_e32 v68, v72, v152
	v_exp_f32_e32 v132, v68
	v_sub_f32_e32 v68, v73, v152
	v_pk_add_f32 v[66:67], v[126:127], v[66:67]
	v_exp_f32_e32 v96, v68
	v_pk_add_f32 v[66:67], v[128:129], v[66:67]
	v_exp_f32_e32 v82, v153
	v_pk_add_f32 v[66:67], v[130:131], v[66:67]
	v_mov_b32_e32 v83, v134
	v_pk_add_f32 v[66:67], v[94:95], v[66:67]
	v_add_u32_e32 v86, v150, v144
	v_pk_add_f32 v[66:67], v[132:133], v[66:67]
	v_pk_mul_f32 v[68:69], v[36:37], v[82:83] op_sel_hi:[1,0]
	v_pk_add_f32 v[66:67], v[96:97], v[66:67]
	v_pk_mul_f32 v[72:73], v[40:41], v[82:83] op_sel_hi:[1,0]
	v_pk_fma_f32 v[104:105], v[104:105], v[82:83], v[66:67]
	v_pk_mul_f32 v[66:67], v[34:35], v[82:83] op_sel_hi:[1,0]
	v_pk_mul_f32 v[70:71], v[38:39], v[82:83] op_sel_hi:[1,0]
	v_pk_mul_f32 v[44:45], v[44:45], v[82:83] op_sel_hi:[1,0]
	v_pk_mul_f32 v[42:43], v[42:43], v[82:83] op_sel_hi:[1,0]
	v_pk_mul_f32 v[36:37], v[48:49], v[82:83] op_sel_hi:[1,0]
	v_pk_mul_f32 v[34:35], v[46:47], v[82:83] op_sel_hi:[1,0]
	v_add_u32_e32 v186, v150, v144
	ds_read_b128 v[154:157], v186 offset:25088
	ds_read_b128 v[158:161], v186 offset:27136
	ds_read_b128 v[162:165], v186 offset:29184
	ds_read_b128 v[166:169], v186 offset:31232
	v_add_u32_e32 v187, v150, v146
	ds_read_b128 v[170:173], v187 offset:27136
	ds_read_b128 v[174:177], v187 offset:25088
	ds_read_b128 v[178:181], v187 offset:29184
	ds_read_b128 v[182:185], v187 offset:31232
	v_cvt_pk_bf16_f32 v54, v111, v113
	v_cvt_pk_bf16_f32 v55, v115, v117
	v_cvt_pk_bf16_f32 v56, v119, v91
	v_cvt_pk_bf16_f32 v57, v121, v93
	v_cvt_pk_bf16_f32 v38, v110, v112
	v_cvt_pk_bf16_f32 v39, v114, v116
	v_cvt_pk_bf16_f32 v40, v118, v90
	v_cvt_pk_bf16_f32 v41, v120, v92
	v_pk_mul_f32 v[60:61], v[60:61], v[134:135] op_sel_hi:[1,0]
	s_waitcnt lgkmcnt(7)
	v_mfma_f32_16x16x32_bf16 v[78:81], v[154:157], v[54:57], v[78:81]
	v_mul_f32_e64 v58, v58, v134
	v_mul_f32_e64 v59, v59, v134
	v_pk_mul_f32 v[52:53], v[64:65], v[134:135] op_sel_hi:[1,0]
	v_pk_mul_f32 v[50:51], v[62:63], v[134:135] op_sel_hi:[1,0]
	v_mfma_f32_16x16x32_bf16 v[66:69], v[154:157], v[38:41], v[66:69]
	v_add_u32_e32 v90, v150, v146
	v_cvt_pk_bf16_f32 v62, v123, v125
	s_waitcnt lgkmcnt(6)
	v_mfma_f32_16x16x32_bf16 v[74:77], v[158:161], v[54:57], v[74:77]
	v_cvt_pk_bf16_f32 v63, v127, v129
	v_cvt_pk_bf16_f32 v64, v131, v95
	v_cvt_pk_bf16_f32 v65, v133, v97
	v_mfma_f32_16x16x32_bf16 v[70:73], v[158:161], v[38:41], v[70:73]
	v_cvt_pk_bf16_f32 v46, v122, v124
	v_cvt_pk_bf16_f32 v47, v126, v128
	s_waitcnt lgkmcnt(5)
	v_mfma_f32_16x16x32_bf16 v[58:61], v[162:165], v[54:57], v[58:61]
	v_cvt_pk_bf16_f32 v48, v130, v94
	v_cvt_pk_bf16_f32 v49, v132, v96
	v_mov_b32_e32 v110, v152
	v_mfma_f32_16x16x32_bf16 v[42:45], v[162:165], v[38:41], v[42:45]
	v_mov_b32_e32 v111, v1
	s_waitcnt lgkmcnt(4)
	v_mfma_f32_16x16x32_bf16 v[86:89], v[166:169], v[54:57], v[50:53]
	v_mfma_f32_16x16x32_bf16 v[82:85], v[166:169], v[38:41], v[34:37]
	s_waitcnt lgkmcnt(2)
	v_mfma_f32_16x16x32_bf16 v[50:53], v[174:177], v[62:65], v[78:81]
	v_mfma_f32_16x16x32_bf16 v[34:37], v[174:177], v[46:49], v[66:69]
	s_waitcnt lgkmcnt(1)
	v_mfma_f32_16x16x32_bf16 v[58:61], v[178:181], v[62:65], v[58:61]
	v_mfma_f32_16x16x32_bf16 v[42:45], v[178:181], v[46:49], v[42:45]
	v_mfma_f32_16x16x32_bf16 v[54:57], v[170:173], v[62:65], v[74:77]
	v_mfma_f32_16x16x32_bf16 v[38:41], v[170:173], v[46:49], v[70:73]
	s_waitcnt lgkmcnt(0)
	v_mfma_f32_16x16x32_bf16 v[62:65], v[182:185], v[62:65], v[86:89]
	v_mfma_f32_16x16x32_bf16 v[46:49], v[182:185], v[46:49], v[82:85]

.LBB0_220:
	s_or_b64 exec, exec, s[82:83]
	v_max_f32_e32 v1, v68, v69
	v_max_f32_e32 v112, v92, v93
	v_max3_f32 v1, v66, v67, v1
	v_max3_f32 v112, v90, v91, v112
	v_max3_f32 v1, v1, s41, v112
	v_max_f32_e32 v112, v84, v85
	v_max_f32_e32 v114, v96, v96
	v_max_f32_e32 v113, v114, v97
	v_max3_f32 v112, v82, v83, v112
	v_max3_f32 v113, v94, v95, v113
	v_max3_f32 v1, v1, v112, v113
	ds_bpermute_b32 v112, v135, v1
	s_waitcnt lgkmcnt(0)
	v_max_f32_e32 v1, v1, v112
	ds_bpermute_b32 v112, v101, v1
	s_waitcnt lgkmcnt(0)
	v_max3_f32 v1, v111, v1, v112
	v_sub_f32_e32 v66, v66, v1
	v_sub_f32_e32 v112, v111, v1
	v_exp_f32_e32 v111, v66
	v_sub_f32_e32 v66, v67, v1
	v_exp_f32_e32 v113, v66
	v_sub_f32_e32 v66, v68, v1
	v_exp_f32_e32 v115, v66
	v_sub_f32_e32 v66, v69, v1
	v_exp_f32_e32 v117, v66
	v_sub_f32_e32 v66, v90, v1
	v_exp_f32_e32 v119, v66
	v_sub_f32_e32 v66, v91, v1
	v_exp_f32_e32 v91, v66
	v_sub_f32_e32 v66, v92, v1
	v_exp_f32_e32 v121, v66
	v_sub_f32_e32 v66, v93, v1
	v_exp_f32_e32 v93, v66
	v_sub_f32_e32 v66, v82, v1
	v_exp_f32_e32 v123, v66
	v_sub_f32_e32 v66, v83, v1
	v_exp_f32_e32 v125, v66
	v_sub_f32_e32 v66, v84, v1
	v_exp_f32_e32 v127, v66
	v_sub_f32_e32 v66, v85, v1
	v_exp_f32_e32 v129, v66
	v_sub_f32_e32 v66, v94, v1
	v_max_f32_e32 v90, v88, v89
	v_max_f32_e32 v92, v76, v77
	v_max3_f32 v90, v86, v87, v90
	v_max3_f32 v92, v74, v75, v92
	v_exp_f32_e32 v131, v66
	v_sub_f32_e32 v66, v95, v1
	v_max3_f32 v90, v90, s41, v92
	v_exp_f32_e32 v95, v66
	v_sub_f32_e32 v66, v96, v1
	v_max_f32_e32 v92, v72, v73
	v_max_f32_e32 v94, v80, v81
	v_max3_f32 v92, v70, v71, v92
	v_max3_f32 v94, v78, v79, v94
	v_max3_f32 v90, v90, v92, v94
	ds_bpermute_b32 v92, v135, v90
	v_exp_f32_e32 v152, v112
	v_exp_f32_e32 v133, v66
	v_sub_f32_e32 v66, v97, v1
	v_exp_f32_e32 v97, v66
	s_waitcnt lgkmcnt(0)
	v_max_f32_e32 v90, v90, v92
	ds_bpermute_b32 v92, v101, v90
	v_pk_mul_f32 v[84:85], v[52:53], v[152:153] op_sel_hi:[1,0]
	v_pk_mul_f32 v[82:83], v[50:51], v[152:153] op_sel_hi:[1,0]
	v_pk_mul_f32 v[68:69], v[56:57], v[152:153] op_sel_hi:[1,0]
	v_pk_mul_f32 v[66:67], v[54:55], v[152:153] op_sel_hi:[1,0]
	s_waitcnt lgkmcnt(0)
	v_max3_f32 v134, v110, v90, v92
	v_sub_f32_e32 v86, v86, v134
	v_pk_mul_f32 v[60:61], v[60:61], v[152:153] op_sel_hi:[1,0]
	v_pk_mul_f32 v[58:59], v[58:59], v[152:153] op_sel_hi:[1,0]
	v_pk_mul_f32 v[52:53], v[64:65], v[152:153] op_sel_hi:[1,0]
	v_pk_mul_f32 v[50:51], v[62:63], v[152:153] op_sel_hi:[1,0]
	v_sub_f32_e32 v153, v110, v134
	v_exp_f32_e32 v110, v86
	v_sub_f32_e32 v86, v87, v134
	v_exp_f32_e32 v112, v86
	v_sub_f32_e32 v86, v88, v134
	v_sub_f32_e32 v74, v74, v134
	v_exp_f32_e32 v114, v86
	v_sub_f32_e32 v86, v89, v134
	v_exp_f32_e32 v118, v74
	v_sub_f32_e32 v74, v75, v134
	v_exp_f32_e32 v116, v86
	v_exp_f32_e32 v90, v74
	v_sub_f32_e32 v74, v76, v134
	v_sub_f32_e32 v70, v70, v134
	v_exp_f32_e32 v120, v74
	v_pk_add_f32 v[74:75], v[110:111], 0 op_sel_hi:[1,0]
	v_exp_f32_e32 v122, v70
	v_sub_f32_e32 v70, v71, v134
	v_pk_add_f32 v[74:75], v[112:113], v[74:75]
	v_exp_f32_e32 v124, v70
	v_sub_f32_e32 v70, v72, v134
	v_pk_add_f32 v[74:75], v[114:115], v[74:75]
	v_sub_f32_e32 v76, v77, v134
	v_exp_f32_e32 v126, v70
	v_sub_f32_e32 v70, v73, v134
	v_pk_add_f32 v[74:75], v[116:117], v[74:75]
	v_exp_f32_e32 v92, v76
	v_exp_f32_e32 v128, v70
	v_sub_f32_e32 v70, v78, v134
	v_pk_add_f32 v[74:75], v[118:119], v[74:75]
	v_exp_f32_e32 v130, v70
	v_sub_f32_e32 v70, v79, v134
	v_pk_add_f32 v[74:75], v[90:91], v[74:75]
	v_exp_f32_e32 v94, v70
	v_sub_f32_e32 v70, v80, v134
	v_pk_add_f32 v[74:75], v[120:121], v[74:75]
	v_exp_f32_e32 v132, v70
	v_sub_f32_e32 v70, v81, v134
	v_exp_f32_e32 v96, v70
	v_pk_add_f32 v[70:71], v[92:93], v[74:75]
	v_exp_f32_e32 v78, v153
	v_pk_add_f32 v[70:71], v[122:123], v[70:71]
	v_mov_b32_e32 v79, v152
	v_pk_add_f32 v[70:71], v[124:125], v[70:71]
	v_add_u32_e32 v86, v150, v144
	v_pk_add_f32 v[70:71], v[126:127], v[70:71]
	v_pk_mul_f32 v[76:77], v[36:37], v[78:79] op_sel_hi:[1,0]
	v_pk_add_f32 v[70:71], v[128:129], v[70:71]
	v_pk_mul_f32 v[74:75], v[34:35], v[78:79] op_sel_hi:[1,0]
	v_pk_add_f32 v[70:71], v[130:131], v[70:71]
	v_pk_mul_f32 v[72:73], v[40:41], v[78:79] op_sel_hi:[1,0]
	v_pk_add_f32 v[70:71], v[94:95], v[70:71]
	v_pk_mul_f32 v[44:45], v[44:45], v[78:79] op_sel_hi:[1,0]
	v_pk_add_f32 v[70:71], v[132:133], v[70:71]
	v_pk_mul_f32 v[42:43], v[42:43], v[78:79] op_sel_hi:[1,0]
	v_pk_add_f32 v[70:71], v[96:97], v[70:71]
	v_pk_mul_f32 v[36:37], v[48:49], v[78:79] op_sel_hi:[1,0]
	v_pk_fma_f32 v[104:105], v[104:105], v[78:79], v[70:71]
	v_pk_mul_f32 v[70:71], v[38:39], v[78:79] op_sel_hi:[1,0]
	v_pk_mul_f32 v[34:35], v[46:47], v[78:79] op_sel_hi:[1,0]
	v_add_u32_e32 v186, v150, v144
	ds_read_b128 v[154:157], v186 offset:33280
	ds_read_b128 v[158:161], v186 offset:35328
	ds_read_b128 v[162:165], v186 offset:37376
	ds_read_b128 v[166:169], v186 offset:39424
	v_add_u32_e32 v187, v150, v146
	ds_read_b128 v[170:173], v187 offset:35328
	ds_read_b128 v[174:177], v187 offset:33280
	ds_read_b128 v[178:181], v187 offset:37376
	ds_read_b128 v[182:185], v187 offset:39424
	v_cvt_pk_bf16_f32 v54, v111, v113
	v_cvt_pk_bf16_f32 v55, v115, v117
	v_cvt_pk_bf16_f32 v56, v119, v91
	v_cvt_pk_bf16_f32 v57, v121, v93
	v_cvt_pk_bf16_f32 v38, v110, v112
	v_cvt_pk_bf16_f32 v39, v114, v116
	v_cvt_pk_bf16_f32 v40, v118, v90
	v_cvt_pk_bf16_f32 v41, v120, v92
	v_add_u32_e32 v90, v150, v146
	s_waitcnt lgkmcnt(7)
	v_mfma_f32_16x16x32_bf16 v[82:85], v[154:157], v[54:57], v[82:85]
	v_cvt_pk_bf16_f32 v62, v123, v125
	v_cvt_pk_bf16_f32 v63, v127, v129
	v_cvt_pk_bf16_f32 v64, v131, v95
	v_mfma_f32_16x16x32_bf16 v[74:77], v[154:157], v[38:41], v[74:77]
	v_cvt_pk_bf16_f32 v65, v133, v97
	v_cvt_pk_bf16_f32 v46, v122, v124
	s_waitcnt lgkmcnt(6)
	v_mfma_f32_16x16x32_bf16 v[66:69], v[158:161], v[54:57], v[66:69]
	v_cvt_pk_bf16_f32 v47, v126, v128
	v_cvt_pk_bf16_f32 v48, v130, v94
	v_cvt_pk_bf16_f32 v49, v132, v96
	v_mfma_f32_16x16x32_bf16 v[70:73], v[158:161], v[38:41], v[70:73]
	v_mov_b32_e32 v110, v134
	v_mov_b32_e32 v111, v1
	s_waitcnt lgkmcnt(5)
	v_mfma_f32_16x16x32_bf16 v[58:61], v[162:165], v[54:57], v[58:61]
	v_mfma_f32_16x16x32_bf16 v[42:45], v[162:165], v[38:41], v[42:45]
	s_waitcnt lgkmcnt(4)
	v_mfma_f32_16x16x32_bf16 v[86:89], v[166:169], v[54:57], v[50:53]
	v_mfma_f32_16x16x32_bf16 v[78:81], v[166:169], v[38:41], v[34:37]
	s_waitcnt lgkmcnt(3)
	v_mfma_f32_16x16x32_bf16 v[54:57], v[170:173], v[62:65], v[66:69]
	s_waitcnt lgkmcnt(1)
	v_mfma_f32_16x16x32_bf16 v[58:61], v[178:181], v[62:65], v[58:61]
	v_mfma_f32_16x16x32_bf16 v[42:45], v[178:181], v[46:49], v[42:45]
	v_mfma_f32_16x16x32_bf16 v[50:53], v[174:177], v[62:65], v[82:85]
	v_mfma_f32_16x16x32_bf16 v[34:37], v[174:177], v[46:49], v[74:77]
	v_mfma_f32_16x16x32_bf16 v[38:41], v[170:173], v[46:49], v[70:73]
	s_waitcnt lgkmcnt(0)
	v_mfma_f32_16x16x32_bf16 v[62:65], v[182:185], v[62:65], v[86:89]
	v_mfma_f32_16x16x32_bf16 v[46:49], v[182:185], v[46:49], v[78:81]
